# NOMAX prompt-FoX loop: the eight P.V MFMAs of the first half-step are interleaved with the 32-exp burst ahead of the barrier (they sat bunched behind it)
# baseline (speedup 1.0000x reference)
.LBB0_1001:
	s_mov_b32 s68, s87
	s_mov_b32 s69, s80
	s_mov_b32 s74, s86
	ds_read_b128 v[100:103], v2
	ds_read_b128 v[104:107], v2 offset:32
	ds_read_b128 v[84:87], v2 offset:128
	ds_read_b128 v[88:91], v2 offset:160
	ds_read_b128 v[108:111], v2 offset:64
	ds_read_b128 v[112:115], v2 offset:96
	ds_read_b128 v[92:95], v2 offset:192
	ds_read_b128 v[96:99], v2 offset:224
	v_add_u32_e32 v16, s75, v209
	ds_read_b64_tr_b16 v[4:5], v16 offset:24576
	ds_read_b64_tr_b16 v[6:7], v16 offset:25088
	v_add_f32_e32 v8, v68, v69
	v_add_f32_e32 v8, v70, v8
	v_add_f32_e32 v8, v71, v8
	v_add_f32_e32 v8, v72, v8
	v_add_f32_e32 v12, v73, v8
	v_cvt_pk_bf16_f32 v144, v68, v69
	v_cvt_pk_bf16_f32 v145, v70, v71
	s_waitcnt lgkmcnt(4)
	v_mfma_f32_32x32x16_bf16 v[100:115], v[176:179], v[128:131], v[100:115]
	ds_read_b64_tr_b16 v[8:9], v16 offset:28672
	ds_read_b64_tr_b16 v[10:11], v16 offset:29184
	v_add_f32_e32 v12, v74, v12
	v_add_f32_e32 v12, v75, v12
	v_add_f32_e32 v12, v76, v12
	v_add_f32_e32 v17, v77, v12
	v_cvt_pk_bf16_f32 v146, v72, v73
	v_cvt_pk_bf16_f32 v147, v74, v75
	s_waitcnt lgkmcnt(4)
	v_mfma_f32_32x32x16_bf16 v[84:99], v[172:175], v[128:131], v[84:99]
	ds_read_b64_tr_b16 v[12:13], v16 offset:25600
	ds_read_b64_tr_b16 v[14:15], v16 offset:26112
	v_add_f32_e32 v17, v78, v17
	v_add_f32_e32 v17, v79, v17
	v_add_f32_e32 v17, v80, v17
	v_add_f32_e32 v17, v81, v17
	v_cvt_pk_bf16_f32 v140, v76, v77
	v_cvt_pk_bf16_f32 v141, v78, v79
	v_mfma_f32_32x32x16_bf16 v[100:115], v[168:171], v[124:127], v[100:115]
	ds_read_b64_tr_b16 v[68:69], v16 offset:29696
	ds_read_b64_tr_b16 v[70:71], v16 offset:30208
	v_add_f32_e32 v17, v82, v17
	v_add_f32_e32 v17, v83, v17
	v_add_f32_e32 v17, v52, v17
	v_add_f32_e32 v17, v53, v17
	v_cvt_pk_bf16_f32 v142, v80, v81
	v_cvt_pk_bf16_f32 v143, v82, v83
	v_mfma_f32_32x32x16_bf16 v[84:99], v[164:167], v[124:127], v[84:99]
	ds_read_b64_tr_b16 v[72:73], v16 offset:26624
	ds_read_b64_tr_b16 v[74:75], v16 offset:27136
	v_add_f32_e32 v17, v54, v17
	v_add_f32_e32 v17, v55, v17
	v_add_f32_e32 v17, v56, v17
	v_add_f32_e32 v17, v57, v17
	v_cvt_pk_bf16_f32 v136, v52, v53
	v_cvt_pk_bf16_f32 v137, v54, v55
	v_mfma_f32_32x32x16_bf16 v[100:115], v[160:163], v[120:123], v[100:115]
	ds_read_b64_tr_b16 v[52:53], v16 offset:30720
	ds_read_b64_tr_b16 v[54:55], v16 offset:31232
	v_add_f32_e32 v17, v58, v17
	v_add_f32_e32 v17, v59, v17
	v_add_f32_e32 v17, v60, v17
	v_add_f32_e32 v17, v61, v17
	v_cvt_pk_bf16_f32 v138, v56, v57
	v_cvt_pk_bf16_f32 v139, v58, v59
	v_mfma_f32_32x32x16_bf16 v[84:99], v[156:159], v[120:123], v[84:99]
	ds_read_b64_tr_b16 v[76:77], v16 offset:27648
	ds_read_b64_tr_b16 v[78:79], v16 offset:28160
	v_add_f32_e32 v17, v62, v17
	v_add_f32_e32 v17, v63, v17
	v_add_f32_e32 v17, v64, v17
	v_add_f32_e32 v17, v65, v17
	v_cvt_pk_bf16_f32 v132, v60, v61
	v_cvt_pk_bf16_f32 v133, v62, v63
	v_mfma_f32_32x32x16_bf16 v[100:115], v[152:155], v[116:119], v[100:115]
	ds_read_b64_tr_b16 v[160:161], v16 offset:31744
	ds_read_b64_tr_b16 v[162:163], v16 offset:32256
	v_add_f32_e32 v16, v66, v17
	v_add_f32_e32 v16, v67, v16
	v_add_f32_e32 v181, 0, v16
	v_cvt_pk_bf16_f32 v134, v64, v65
	v_cvt_pk_bf16_f32 v135, v66, v67
	v_mfma_f32_32x32x16_bf16 v[84:99], v[148:151], v[116:119], v[84:99]
	s_add_i32 s75, s0, s80
	s_add_i32 s80, s75, -2
	s_ashr_i32 s81, s80, 31
	s_lshl_b64 s[80:81], s[80:81], 16
	v_lshl_add_u64 v[16:17], v[200:201], 0, s[80:81]
	s_add_i32 s80, s86, s85
	s_mov_b32 s81, m0
	s_mov_b32 m0, s80
	s_nop 0
	global_load_lds_dwordx4 v[16:17], off
	s_mov_b32 m0, s81
	s_add_i32 s80, s75, -4
	s_ashr_i32 s81, s80, 31
	s_lshl_b64 s[80:81], s[80:81], 16
	v_lshl_add_u64 v[16:17], v[202:203], 0, s[80:81]
	s_add_i32 s80, s87, s89
	s_mov_b32 s81, m0
	s_mov_b32 m0, s80
	s_nop 0
	global_load_lds_dwordx4 v[16:17], off
	s_mov_b32 m0, s81
	s_waitcnt lgkmcnt(0)
	v_mfma_f32_32x32x16_bf16 v[20:35], v[144:147], v[4:7], v[20:35]
	v_exp_f32_e32 v100, v100
	v_exp_f32_e32 v101, v101
	v_exp_f32_e32 v102, v102
	v_exp_f32_e32 v103, v103
	s_nop 0
	v_mfma_f32_32x32x16_bf16 v[36:51], v[144:147], v[8:11], v[36:51]
	v_exp_f32_e32 v104, v104
	v_exp_f32_e32 v105, v105
	v_exp_f32_e32 v106, v106
	v_exp_f32_e32 v107, v107
	v_add_u32_e32 v16, s68, v208
	ds_read_b128 v[172:175], v16
	ds_read_b128 v[176:179], v16 offset:512
	v_mfma_f32_32x32x16_bf16 v[20:35], v[140:143], v[12:15], v[20:35]
	v_exp_f32_e32 v108, v108
	v_exp_f32_e32 v109, v109
	v_exp_f32_e32 v110, v110
	v_exp_f32_e32 v111, v111
	ds_read_b128 v[182:185], v16 offset:2048
	ds_read_b128 v[168:171], v16 offset:2560
	v_mfma_f32_32x32x16_bf16 v[36:51], v[140:143], v[68:71], v[36:51]
	v_exp_f32_e32 v112, v112
	v_exp_f32_e32 v113, v113
	v_exp_f32_e32 v114, v114
	v_exp_f32_e32 v115, v115
	ds_read_b128 v[164:167], v16 offset:4096
	ds_read_b128 v[156:159], v16 offset:4608
	v_mfma_f32_32x32x16_bf16 v[20:35], v[136:139], v[72:75], v[20:35]
	v_exp_f32_e32 v84, v84
	v_exp_f32_e32 v85, v85
	v_exp_f32_e32 v86, v86
	v_exp_f32_e32 v87, v87
	ds_read_b128 v[152:155], v16 offset:6144
	ds_read_b128 v[148:151], v16 offset:6656
	v_mfma_f32_32x32x16_bf16 v[36:51], v[136:139], v[52:55], v[36:51]
	v_exp_f32_e32 v88, v88
	v_exp_f32_e32 v89, v89
	v_exp_f32_e32 v90, v90
	v_exp_f32_e32 v91, v91
	s_nop 0
	v_mfma_f32_32x32x16_bf16 v[20:35], v[132:135], v[76:79], v[20:35]
	v_exp_f32_e32 v92, v92
	v_exp_f32_e32 v93, v93
	v_exp_f32_e32 v94, v94
	v_exp_f32_e32 v95, v95
	s_nop 0
	v_mfma_f32_32x32x16_bf16 v[36:51], v[132:135], v[160:163], v[36:51]
	v_exp_f32_e32 v96, v96
	v_exp_f32_e32 v97, v97
	v_exp_f32_e32 v98, v98
	v_exp_f32_e32 v99, v99
	s_waitcnt vmcnt(2) lgkmcnt(0)
	s_barrier
; #define TWAIT_BAR(N) asm volatile("s_waitcnt vmcnt(" #N ") lgkmcnt(0)\n\ts_barrier" ::: "memory")
; #define RESC() do { if constexpr (!NOMAX) if (resc) { asm volatile("s_waitcnt lgkmcnt(0)" ::: "memory"); \
;         _Pragma("unroll") for (int d_ = 0; d_ < 2; ++d_) _Pragma("unroll") for (int r = 0; r < 16; ++r) o[d_][r] *= wsf[crow(r, hi)]; } } while (0)
; #define ROT() do { sl_prev = sl_cur; sl_cur = sl_next; sl_next = (sl_next == 2 * SLOTB) ? 0 : sl_next + SLOTB; } while (0)
; #define RESC() do { if constexpr (!NOMAX) if (resc) { asm volatile("s_waitcnt lgkmcnt(0)" ::: "memory"); \
;         _Pragma("unroll") for (int d_ = 0; d_ < 4; ++d_) _Pragma("unroll") for (int r = 0; r < 16; ++r) o[d_][r] *= wsf[crow(r, hi)]; } } while (0)
; #define ROT() do { sl_prev = sl_cur; sl_cur = sl_next; sl_next = (sl_next == 2) ? 0 : sl_next + 1; } while (0)
; #define RESC() do { if (resc) { asm volatile("s_waitcnt lgkmcnt(0)" ::: "memory"); \
;         _Pragma("unroll") for (int d_ = 0; d_ < 4; ++d_) _Pragma("unroll") for (int r = 0; r < 16; ++r) o[d_][r] *= wsf[crow(r, hi)]; } } while (0)
; template <bool NOMAX>
; __device__ __forceinline__ void fox_unit(const AttnCtx& C, int u, LAS unsigned char* lds) {
;     ...
;     int kk = 1;
;     for (; kk + 5 < n; kk += 2) {
;         STEP(pB0, pB1, pA0, pA1, kk, true, true, true, false);     TWAIT_BAR(2); RESC(); ROT();
;         STEP(pA0, pA1, pB0, pB1, kk + 1, true, true, true, false); TWAIT_BAR(2); RESC(); ROT();
;     }
	s_add_i32 s80, s87, 0x2000
	s_waitcnt lgkmcnt(14)
	s_cmpk_lg_i32 s87, 0x4000
	s_cselect_b32 s86, s80, 0
	v_add_f32_e32 v16, v212, v181
	v_add_u32_e32 v17, s74, v209
	s_waitcnt lgkmcnt(12)
	ds_read_b128 v[68:71], v2 offset:256
	ds_read_b128 v[72:75], v2 offset:288
	ds_read_b128 v[52:55], v2 offset:384
	ds_read_b128 v[56:59], v2 offset:416
	s_waitcnt lgkmcnt(14)
	ds_read_b128 v[76:79], v2 offset:320
	ds_read_b128 v[80:83], v2 offset:352
	ds_read_b128 v[60:63], v2 offset:448
	ds_read_b128 v[64:67], v2 offset:480
	s_waitcnt lgkmcnt(14)
	ds_read_b64_tr_b16 v[4:5], v17 offset:24576
	ds_read_b64_tr_b16 v[6:7], v17 offset:25088
	s_waitcnt lgkmcnt(4)
	v_mfma_f32_32x32x16_bf16 v[68:83], v[172:175], v[128:131], v[68:83]
	v_add_f32_e32 v8, v100, v101
	v_add_f32_e32 v8, v102, v8
	v_add_f32_e32 v8, v103, v8
	v_add_f32_e32 v8, v104, v8
	v_add_f32_e32 v12, v105, v8
	v_cvt_pk_bf16_f32 v144, v100, v101
	v_cvt_pk_bf16_f32 v145, v102, v103
	ds_read_b64_tr_b16 v[8:9], v17 offset:28672
	ds_read_b64_tr_b16 v[10:11], v17 offset:29184
	s_waitcnt lgkmcnt(4)
	v_mfma_f32_32x32x16_bf16 v[52:67], v[176:179], v[128:131], v[52:67]
	v_add_f32_e32 v12, v106, v12
	v_add_f32_e32 v12, v107, v12
	v_add_f32_e32 v12, v108, v12
	v_add_f32_e32 v100, v109, v12
	v_cvt_pk_bf16_f32 v146, v104, v105
	v_cvt_pk_bf16_f32 v147, v106, v107
	ds_read_b64_tr_b16 v[12:13], v17 offset:25600
	ds_read_b64_tr_b16 v[14:15], v17 offset:26112
	v_mfma_f32_32x32x16_bf16 v[68:83], v[182:185], v[124:127], v[68:83]
	v_add_f32_e32 v100, v110, v100
	v_add_f32_e32 v100, v111, v100
	v_add_f32_e32 v100, v112, v100
	v_add_f32_e32 v104, v113, v100
	v_cvt_pk_bf16_f32 v140, v108, v109
	v_cvt_pk_bf16_f32 v141, v110, v111
	ds_read_b64_tr_b16 v[100:101], v17 offset:29696
	ds_read_b64_tr_b16 v[102:103], v17 offset:30208
	v_mfma_f32_32x32x16_bf16 v[52:67], v[168:171], v[124:127], v[52:67]
	v_add_f32_e32 v104, v114, v104
	v_add_f32_e32 v104, v115, v104
	v_add_f32_e32 v104, v84, v104
	v_add_f32_e32 v108, v85, v104
	v_cvt_pk_bf16_f32 v142, v112, v113
	v_cvt_pk_bf16_f32 v143, v114, v115
	ds_read_b64_tr_b16 v[104:105], v17 offset:26624
	ds_read_b64_tr_b16 v[106:107], v17 offset:27136
	v_mfma_f32_32x32x16_bf16 v[68:83], v[164:167], v[120:123], v[68:83]
	v_add_f32_e32 v108, v86, v108
	v_add_f32_e32 v108, v87, v108
	v_add_f32_e32 v108, v88, v108
	v_add_f32_e32 v108, v89, v108
	v_cvt_pk_bf16_f32 v136, v84, v85
	v_cvt_pk_bf16_f32 v137, v86, v87
	ds_read_b64_tr_b16 v[84:85], v17 offset:30720
	ds_read_b64_tr_b16 v[86:87], v17 offset:31232
	v_mfma_f32_32x32x16_bf16 v[52:67], v[156:159], v[120:123], v[52:67]
	v_add_f32_e32 v108, v90, v108
	v_add_f32_e32 v108, v91, v108
	v_add_f32_e32 v108, v92, v108
	v_add_f32_e32 v108, v93, v108
	v_cvt_pk_bf16_f32 v138, v88, v89
	v_cvt_pk_bf16_f32 v139, v90, v91
	ds_read_b64_tr_b16 v[88:89], v17 offset:27648
	ds_read_b64_tr_b16 v[90:91], v17 offset:28160
	v_mfma_f32_32x32x16_bf16 v[68:83], v[152:155], v[116:119], v[68:83]
	v_add_f32_e32 v108, v94, v108
	v_add_f32_e32 v108, v95, v108
	v_add_f32_e32 v108, v96, v108
	v_add_f32_e32 v108, v97, v108
	v_cvt_pk_bf16_f32 v132, v92, v93
	v_cvt_pk_bf16_f32 v133, v94, v95
	ds_read_b64_tr_b16 v[92:93], v17 offset:31744
	ds_read_b64_tr_b16 v[94:95], v17 offset:32256
	v_mfma_f32_32x32x16_bf16 v[52:67], v[148:151], v[116:119], v[52:67]
	v_add_f32_e32 v17, v98, v108
	v_add_f32_e32 v17, v99, v17
	v_add_f32_e32 v17, 0, v17
	v_cvt_pk_bf16_f32 v134, v96, v97
	v_cvt_pk_bf16_f32 v135, v98, v99
	s_add_i32 s80, s75, -1
	s_ashr_i32 s81, s80, 31
	s_lshl_b64 s[80:81], s[80:81], 16
	s_add_i32 s74, s87, s85
	v_add_f32_e32 v212, v16, v17
	v_lshl_add_u64 v[16:17], v[200:201], 0, s[80:81]
	s_mov_b32 s80, m0
	s_mov_b32 m0, s74
	s_nop 0
	global_load_lds_dwordx4 v[16:17], off
	s_mov_b32 m0, s80
	s_add_i32 s74, s75, -3
	s_ashr_i32 s75, s74, 31
	s_lshl_b64 s[74:75], s[74:75], 16
	v_lshl_add_u64 v[16:17], v[202:203], 0, s[74:75]
	s_add_i32 s74, s86, s89
	s_mov_b32 s75, m0
	s_mov_b32 m0, s74
	s_nop 0
	global_load_lds_dwordx4 v[16:17], off
	s_mov_b32 m0, s75
	s_waitcnt lgkmcnt(14)
	v_mfma_f32_32x32x16_bf16 v[20:35], v[144:147], v[4:7], v[20:35]
	v_exp_f32_e32 v68, v68
	v_exp_f32_e32 v69, v69
	v_exp_f32_e32 v70, v70
	v_exp_f32_e32 v71, v71
	s_waitcnt lgkmcnt(12)
	v_mfma_f32_32x32x16_bf16 v[36:51], v[144:147], v[8:11], v[36:51]
	v_exp_f32_e32 v72, v72
	v_exp_f32_e32 v73, v73
	v_exp_f32_e32 v74, v74
	v_exp_f32_e32 v75, v75
	v_add_u32_e32 v4, s86, v208
	ds_read_b128 v[176:179], v4
	ds_read_b128 v[172:175], v4 offset:512
	s_waitcnt lgkmcnt(12)
	v_mfma_f32_32x32x16_bf16 v[20:35], v[140:143], v[12:15], v[20:35]
	v_exp_f32_e32 v76, v76
	v_exp_f32_e32 v77, v77
	v_exp_f32_e32 v78, v78
	v_exp_f32_e32 v79, v79
	ds_read_b128 v[168:171], v4 offset:2048
	ds_read_b128 v[164:167], v4 offset:2560
	s_waitcnt lgkmcnt(12)
	v_mfma_f32_32x32x16_bf16 v[36:51], v[140:143], v[100:103], v[36:51]
	v_exp_f32_e32 v80, v80
	v_exp_f32_e32 v81, v81
	v_exp_f32_e32 v82, v82
	v_exp_f32_e32 v83, v83
	ds_read_b128 v[160:163], v4 offset:4096
	ds_read_b128 v[156:159], v4 offset:4608
	s_waitcnt lgkmcnt(12)
	v_mfma_f32_32x32x16_bf16 v[20:35], v[136:139], v[104:107], v[20:35]
	v_exp_f32_e32 v52, v52
	v_exp_f32_e32 v53, v53
	v_exp_f32_e32 v54, v54
	v_exp_f32_e32 v55, v55
	ds_read_b128 v[152:155], v4 offset:6144
	ds_read_b128 v[148:151], v4 offset:6656
	s_waitcnt lgkmcnt(12)
	v_mfma_f32_32x32x16_bf16 v[36:51], v[136:139], v[84:87], v[36:51]
	v_exp_f32_e32 v56, v56
	v_exp_f32_e32 v57, v57
	v_exp_f32_e32 v58, v58
	v_exp_f32_e32 v59, v59
	s_waitcnt lgkmcnt(10)
	v_mfma_f32_32x32x16_bf16 v[20:35], v[132:135], v[88:91], v[20:35]
	v_exp_f32_e32 v60, v60
	v_exp_f32_e32 v61, v61
	v_exp_f32_e32 v62, v62
	v_exp_f32_e32 v63, v63
	s_waitcnt lgkmcnt(8)
	v_mfma_f32_32x32x16_bf16 v[36:51], v[132:135], v[92:95], v[36:51]
	v_exp_f32_e32 v64, v64
	v_exp_f32_e32 v65, v65
	v_exp_f32_e32 v66, v66
	v_exp_f32_e32 v67, v67
	s_add_i32 s74, s86, 0x2000
	s_waitcnt vmcnt(2) lgkmcnt(0)
	s_barrier
	s_cmpk_lg_i32 s86, 0x4000
	s_cselect_b32 s87, s74, 0
	s_add_i32 s80, s69, 2
	v_add_u32_e32 v2, 0x200, v2
	s_cmp_ge_i32 s80, s76
	s_mov_b32 s75, s68
	s_cbranch_scc0 .LBB0_1001
	s_add_i32 s88, s69, -3
	s_add_i32 s69, s88, 1
	s_cmp_ge_i32 s69, s76
	s_cbranch_scc0 .LBB0_1008
